# GEMM K-loop heads aligned to 256 bytes
# baseline (speedup 1.0000x reference)
; template <class Epi, class Sched>
; __device__ __forceinline__ void gemm_phase(LAS unsigned char* lds, const Gemm g, const Sched& S, const Epi& E) {
;     ...
;         const bool has_next = S.next(ui + 1, nxt);
;         const size_t nko = (has_next && nxt.kc > 0) ? (size_t)nxt.kc * nts * kstep : 0;
;         const char* nA = has_next ? (const char*)g.A + (size_t)nxt.pm * tstep + nko : cA; const char* nB = has_next ? (const char*)g.Bt + (size_t)nxt.pn * tstep + nko : cB;
;         const int nt = cur.kc >= 0 ? nts : ntf;
;         for (int t = 0; t < nt; t += 2) {
;     ...
; #pragma unroll
;         for (int a = 0; a < 2; ++a)
; #pragma unroll
;             for (int b = 0; b < 2; ++b)
; #pragma unroll
;                 for (int m = 0; m < 4; ++m)
; #pragma unroll
;                     for (int n = 0; n < 2; ++n) acc[a][b][m][n] = (f32x4){0.f, 0.f, 0.f, 0.f};
.LBB0_502:
	s_ashr_i32 s51, s50, 31
	s_lshl_b64 s[12:13], s[50:51], 19
	s_add_u32 s54, s92, s12
	s_addc_u32 s55, s93, s13
	s_and_b64 s[12:13], s[38:39], exec
	s_cselect_b32 s7, s55, s15
	s_cselect_b32 s8, s54, s14
	s_ashr_i32 s53, s52, 31
	s_lshl_b64 s[12:13], s[52:53], 19
	s_add_u32 s56, s24, s12
	s_addc_u32 s57, s25, s13
	s_and_b64 s[12:13], s[38:39], exec
	s_cselect_b32 s12, s57, s17
	s_cselect_b32 s13, s56, s16
	s_add_u32 s14, s14, 0x40080
	s_addc_u32 s15, s15, 0
	s_add_u32 s21, s16, 0x100
	v_mov_b32_e32 v0, 0
	s_addc_u32 s33, s17, 0
	s_mov_b32 s40, -2
	v_mov_b32_e32 v1, v0
	s_waitcnt lgkmcnt(0)
	v_mov_b32_e32 v2, v0
	v_mov_b32_e32 v3, v0
	v_mov_b32_e32 v4, v0
	v_mov_b32_e32 v5, v0
	v_mov_b32_e32 v6, v0
	v_mov_b32_e32 v7, v0
	v_mov_b32_e32 v16, v0
	v_mov_b32_e32 v17, v0
	v_mov_b32_e32 v18, v0
	v_mov_b32_e32 v19, v0
	v_mov_b32_e32 v20, v0
	v_mov_b32_e32 v21, v0
	v_mov_b32_e32 v22, v0
	v_mov_b32_e32 v23, v0
	v_mov_b32_e32 v32, v0
	v_mov_b32_e32 v33, v0
	v_mov_b32_e32 v34, v0
	v_mov_b32_e32 v35, v0
	v_mov_b32_e32 v36, v0
	v_mov_b32_e32 v37, v0
	v_mov_b32_e32 v38, v0
	v_mov_b32_e32 v39, v0
	v_mov_b32_e32 v48, v0
	v_mov_b32_e32 v49, v0
	v_mov_b32_e32 v50, v0
	v_mov_b32_e32 v51, v0
	v_mov_b32_e32 v52, v0
	v_mov_b32_e32 v53, v0
	v_mov_b32_e32 v54, v0
	v_mov_b32_e32 v55, v0
	v_mov_b32_e32 v8, v0
	v_mov_b32_e32 v9, v0
	v_mov_b32_e32 v10, v0
	v_mov_b32_e32 v11, v0
	v_mov_b32_e32 v12, v0
	v_mov_b32_e32 v13, v0
	v_mov_b32_e32 v14, v0
	v_mov_b32_e32 v15, v0
	v_mov_b32_e32 v24, v0
	v_mov_b32_e32 v25, v0
	v_mov_b32_e32 v26, v0
	v_mov_b32_e32 v27, v0
	v_mov_b32_e32 v28, v0
	v_mov_b32_e32 v29, v0
	v_mov_b32_e32 v30, v0
	v_mov_b32_e32 v31, v0
	v_mov_b32_e32 v40, v0
	v_mov_b32_e32 v41, v0
	v_mov_b32_e32 v42, v0
	v_mov_b32_e32 v43, v0
	v_mov_b32_e32 v44, v0
	v_mov_b32_e32 v45, v0
	v_mov_b32_e32 v46, v0
	v_mov_b32_e32 v47, v0
	v_mov_b32_e32 v56, v0
	v_mov_b32_e32 v57, v0
	v_mov_b32_e32 v58, v0
	v_mov_b32_e32 v59, v0
	v_mov_b32_e32 v60, v0
	v_mov_b32_e32 v61, v0
	v_mov_b32_e32 v62, v0
	v_mov_b32_e32 v63, v0
	v_mov_b32_e32 v64, v0
	v_mov_b32_e32 v65, v0
	v_mov_b32_e32 v66, v0
	v_mov_b32_e32 v67, v0
	v_mov_b32_e32 v68, v0
	v_mov_b32_e32 v69, v0
	v_mov_b32_e32 v70, v0
	v_mov_b32_e32 v71, v0
	v_mov_b32_e32 v96, v0
	v_mov_b32_e32 v97, v0
	v_mov_b32_e32 v98, v0
	v_mov_b32_e32 v99, v0
	v_mov_b32_e32 v100, v0
	v_mov_b32_e32 v101, v0
	v_mov_b32_e32 v102, v0
	v_mov_b32_e32 v103, v0
	v_mov_b32_e32 v112, v0
	v_mov_b32_e32 v113, v0
	v_mov_b32_e32 v114, v0
	v_mov_b32_e32 v115, v0
	v_mov_b32_e32 v116, v0
	v_mov_b32_e32 v117, v0
	v_mov_b32_e32 v118, v0
	v_mov_b32_e32 v119, v0
	v_mov_b32_e32 v128, v0
	v_mov_b32_e32 v129, v0
	v_mov_b32_e32 v130, v0
	v_mov_b32_e32 v131, v0
	v_mov_b32_e32 v132, v0
	v_mov_b32_e32 v133, v0
	v_mov_b32_e32 v134, v0
	v_mov_b32_e32 v135, v0
	v_mov_b32_e32 v88, v0
	v_mov_b32_e32 v89, v0
	v_mov_b32_e32 v90, v0
	v_mov_b32_e32 v91, v0
	v_mov_b32_e32 v92, v0
	v_mov_b32_e32 v93, v0
	v_mov_b32_e32 v94, v0
	v_mov_b32_e32 v95, v0
	v_mov_b32_e32 v104, v0
	v_mov_b32_e32 v105, v0
	v_mov_b32_e32 v106, v0
	v_mov_b32_e32 v107, v0
	v_mov_b32_e32 v108, v0
	v_mov_b32_e32 v109, v0
	v_mov_b32_e32 v110, v0
	v_mov_b32_e32 v111, v0
	v_mov_b32_e32 v120, v0
	v_mov_b32_e32 v121, v0
	v_mov_b32_e32 v122, v0
	v_mov_b32_e32 v123, v0
	v_mov_b32_e32 v124, v0
	v_mov_b32_e32 v125, v0
	v_mov_b32_e32 v126, v0
	v_mov_b32_e32 v127, v0
	v_mov_b32_e32 v136, v0
	v_mov_b32_e32 v137, v0
	v_mov_b32_e32 v138, v0
	v_mov_b32_e32 v139, v0
	v_mov_b32_e32 v140, v0
	v_mov_b32_e32 v141, v0
	v_mov_b32_e32 v142, v0
	v_mov_b32_e32 v143, v0
	.p2align	8

; template <class Epi, class Sched>
; __device__ __forceinline__ void gemm_phase(LAS unsigned char* lds, const Gemm g, const Sched& S, const Epi& E) {
;     ...
;         const int nt = cur.kc >= 0 ? nts : ntf;
;         for (int t = 0; t < nt; t += 2) {
;     ...
; #pragma unroll
;         for (int a = 0; a < 2; ++a)
; #pragma unroll
;             for (int b = 0; b < 2; ++b)
; #pragma unroll
;                 for (int m = 0; m < 4; ++m)
; #pragma unroll
;                     for (int n = 0; n < 2; ++n) acc[a][b][m][n] = (f32x4){0.f, 0.f, 0.f, 0.f};
.LBB0_598:
	s_cmp_lt_i32 s78, 0
	s_cselect_b32 s8, s22, s23
	s_add_i32 s12, s8, -2
	s_add_u32 s6, s6, 0x80
	s_addc_u32 s7, s7, 0
	s_add_u32 s13, s14, 0x100
	v_mov_b32_e32 v0, 0
	s_mov_b32 s17, 0
	s_addc_u32 s16, s15, 0
	v_mov_b32_e32 v1, v0
	v_mov_b32_e32 v2, v0
	v_mov_b32_e32 v3, v0
	v_mov_b32_e32 v4, v0
	v_mov_b32_e32 v5, v0
	v_mov_b32_e32 v6, v0
	v_mov_b32_e32 v7, v0
	v_mov_b32_e32 v8, v0
	v_mov_b32_e32 v9, v0
	v_mov_b32_e32 v10, v0
	v_mov_b32_e32 v11, v0
	v_mov_b32_e32 v12, v0
	v_mov_b32_e32 v13, v0
	v_mov_b32_e32 v14, v0
	v_mov_b32_e32 v15, v0
	v_mov_b32_e32 v24, v0
	v_mov_b32_e32 v25, v0
	v_mov_b32_e32 v26, v0
	v_mov_b32_e32 v27, v0
	v_mov_b32_e32 v28, v0
	v_mov_b32_e32 v29, v0
	v_mov_b32_e32 v30, v0
	v_mov_b32_e32 v31, v0
	v_mov_b32_e32 v40, v0
	v_mov_b32_e32 v41, v0
	v_mov_b32_e32 v42, v0
	v_mov_b32_e32 v43, v0
	v_mov_b32_e32 v44, v0
	v_mov_b32_e32 v45, v0
	v_mov_b32_e32 v46, v0
	v_mov_b32_e32 v47, v0
	v_mov_b32_e32 v16, v0
	v_mov_b32_e32 v17, v0
	v_mov_b32_e32 v18, v0
	v_mov_b32_e32 v19, v0
	v_mov_b32_e32 v20, v0
	v_mov_b32_e32 v21, v0
	v_mov_b32_e32 v22, v0
	v_mov_b32_e32 v23, v0
	v_mov_b32_e32 v32, v0
	v_mov_b32_e32 v33, v0
	v_mov_b32_e32 v34, v0
	v_mov_b32_e32 v35, v0
	v_mov_b32_e32 v36, v0
	v_mov_b32_e32 v37, v0
	v_mov_b32_e32 v38, v0
	v_mov_b32_e32 v39, v0
	v_mov_b32_e32 v48, v0
	v_mov_b32_e32 v49, v0
	v_mov_b32_e32 v50, v0
	v_mov_b32_e32 v51, v0
	v_mov_b32_e32 v52, v0
	v_mov_b32_e32 v53, v0
	v_mov_b32_e32 v54, v0
	v_mov_b32_e32 v55, v0
	v_mov_b32_e32 v56, v0
	v_mov_b32_e32 v57, v0
	v_mov_b32_e32 v58, v0
	v_mov_b32_e32 v59, v0
	v_mov_b32_e32 v60, v0
	v_mov_b32_e32 v61, v0
	v_mov_b32_e32 v62, v0
	v_mov_b32_e32 v63, v0
	v_mov_b32_e32 v64, v0
	v_mov_b32_e32 v65, v0
	v_mov_b32_e32 v66, v0
	v_mov_b32_e32 v67, v0
	v_mov_b32_e32 v68, v0
	v_mov_b32_e32 v69, v0
	v_mov_b32_e32 v70, v0
	v_mov_b32_e32 v71, v0
	v_mov_b32_e32 v72, v0
	v_mov_b32_e32 v73, v0
	v_mov_b32_e32 v74, v0
	v_mov_b32_e32 v75, v0
	v_mov_b32_e32 v76, v0
	v_mov_b32_e32 v77, v0
	v_mov_b32_e32 v78, v0
	v_mov_b32_e32 v79, v0
	v_mov_b32_e32 v84, v0
	v_mov_b32_e32 v85, v0
	v_mov_b32_e32 v86, v0
	v_mov_b32_e32 v87, v0
	v_mov_b32_e32 v92, v0
	v_mov_b32_e32 v93, v0
	v_mov_b32_e32 v94, v0
	v_mov_b32_e32 v95, v0
	v_mov_b32_e32 v100, v0
	v_mov_b32_e32 v101, v0
	v_mov_b32_e32 v102, v0
	v_mov_b32_e32 v103, v0
	v_mov_b32_e32 v108, v0
	v_mov_b32_e32 v109, v0
	v_mov_b32_e32 v110, v0
	v_mov_b32_e32 v111, v0
	v_mov_b32_e32 v80, v0
	v_mov_b32_e32 v81, v0
	v_mov_b32_e32 v82, v0
	v_mov_b32_e32 v83, v0
	v_mov_b32_e32 v88, v0
	v_mov_b32_e32 v89, v0
	v_mov_b32_e32 v90, v0
	v_mov_b32_e32 v91, v0
	v_mov_b32_e32 v96, v0
	v_mov_b32_e32 v97, v0
	v_mov_b32_e32 v98, v0
	v_mov_b32_e32 v99, v0
	v_mov_b32_e32 v104, v0
	v_mov_b32_e32 v105, v0
	v_mov_b32_e32 v106, v0
	v_mov_b32_e32 v107, v0
	v_mov_b32_e32 v112, v0
	v_mov_b32_e32 v113, v0
	v_mov_b32_e32 v114, v0
	v_mov_b32_e32 v115, v0
	v_mov_b32_e32 v116, v0
	v_mov_b32_e32 v117, v0
	v_mov_b32_e32 v118, v0
	v_mov_b32_e32 v119, v0
	v_mov_b32_e32 v120, v0
	v_mov_b32_e32 v121, v0
	v_mov_b32_e32 v122, v0
	v_mov_b32_e32 v123, v0
	v_mov_b32_e32 v124, v0
	v_mov_b32_e32 v125, v0
	v_mov_b32_e32 v126, v0
	v_mov_b32_e32 v127, v0
	.p2align	8

; template <class Epi, class Sched>
; __device__ __forceinline__ void gemm_phase(LAS unsigned char* lds, const Gemm g, const Sched& S, const Epi& E) {
;     ...
;         const bool has_next = S.next(ui + 1, nxt);
;         const size_t nko = (has_next && nxt.kc > 0) ? (size_t)nxt.kc * nts * kstep : 0;
;         const char* nA = has_next ? (const char*)g.A + (size_t)nxt.pm * tstep + nko : cA; const char* nB = has_next ? (const char*)g.Bt + (size_t)nxt.pn * tstep + nko : cB;
;         const int nt = cur.kc >= 0 ? nts : ntf;
;         for (int t = 0; t < nt; t += 2) {
;     ...
; #pragma unroll
;         for (int a = 0; a < 2; ++a)
; #pragma unroll
;             for (int b = 0; b < 2; ++b)
; #pragma unroll
;                 for (int m = 0; m < 4; ++m)
; #pragma unroll
;                     for (int n = 0; n < 2; ++n) acc[a][b][m][n] = (f32x4){0.f, 0.f, 0.f, 0.f};
.LBB0_743:
	s_ashr_i32 s15, s14, 31
	s_lshl_b64 s[18:19], s[14:15], 19
	s_add_u32 s18, s92, s18
	s_addc_u32 s19, s93, s19
	s_and_b64 s[20:21], s[38:39], exec
	s_cselect_b32 s15, s19, s23
	s_cselect_b32 s44, s18, s22
	s_ashr_i32 s17, s16, 31
	s_lshl_b64 s[20:21], s[16:17], 19
	s_add_u32 s20, s9, s20
	s_addc_u32 s21, s12, s21
	s_and_b64 s[26:27], s[38:39], exec
	s_cselect_b32 s17, s21, s25
	s_cselect_b32 s45, s20, s24
	s_add_u32 s22, s22, 0x40080
	s_addc_u32 s23, s23, 0
	s_add_u32 s46, s24, 0x100
	v_mov_b32_e32 v4, 0
	s_addc_u32 s47, s25, 0
	s_mov_b32 s48, -2
	v_mov_b32_e32 v5, v4
	v_mov_b32_e32 v6, v4
	v_mov_b32_e32 v7, v4
	v_mov_b32_e32 v0, v4
	v_mov_b32_e32 v1, v4
	v_mov_b32_e32 v2, v4
	v_mov_b32_e32 v3, v4
	v_mov_b32_e32 v20, v4
	v_mov_b32_e32 v21, v4
	v_mov_b32_e32 v22, v4
	v_mov_b32_e32 v23, v4
	v_mov_b32_e32 v16, v4
	v_mov_b32_e32 v17, v4
	v_mov_b32_e32 v18, v4
	v_mov_b32_e32 v19, v4
	v_mov_b32_e32 v36, v4
	v_mov_b32_e32 v37, v4
	v_mov_b32_e32 v38, v4
	v_mov_b32_e32 v39, v4
	v_mov_b32_e32 v32, v4
	v_mov_b32_e32 v33, v4
	v_mov_b32_e32 v34, v4
	v_mov_b32_e32 v35, v4
	v_mov_b32_e32 v52, v4
	v_mov_b32_e32 v53, v4
	v_mov_b32_e32 v54, v4
	v_mov_b32_e32 v55, v4
	v_mov_b32_e32 v48, v4
	v_mov_b32_e32 v49, v4
	v_mov_b32_e32 v50, v4
	v_mov_b32_e32 v51, v4
	v_mov_b32_e32 v8, v4
	v_mov_b32_e32 v9, v4
	v_mov_b32_e32 v10, v4
	v_mov_b32_e32 v11, v4
	v_mov_b32_e32 v12, v4
	v_mov_b32_e32 v13, v4
	v_mov_b32_e32 v14, v4
	v_mov_b32_e32 v15, v4
	v_mov_b32_e32 v24, v4
	v_mov_b32_e32 v25, v4
	v_mov_b32_e32 v26, v4
	v_mov_b32_e32 v27, v4
	v_mov_b32_e32 v28, v4
	v_mov_b32_e32 v29, v4
	v_mov_b32_e32 v30, v4
	v_mov_b32_e32 v31, v4
	v_mov_b32_e32 v40, v4
	v_mov_b32_e32 v41, v4
	v_mov_b32_e32 v42, v4
	v_mov_b32_e32 v43, v4
	v_mov_b32_e32 v44, v4
	v_mov_b32_e32 v45, v4
	v_mov_b32_e32 v46, v4
	v_mov_b32_e32 v47, v4
	v_mov_b32_e32 v56, v4
	v_mov_b32_e32 v57, v4
	v_mov_b32_e32 v58, v4
	v_mov_b32_e32 v59, v4
	v_mov_b32_e32 v60, v4
	v_mov_b32_e32 v61, v4
	v_mov_b32_e32 v62, v4
	v_mov_b32_e32 v63, v4
	v_mov_b32_e32 v68, v4
	v_mov_b32_e32 v69, v4
	v_mov_b32_e32 v70, v4
	v_mov_b32_e32 v71, v4
	v_mov_b32_e32 v64, v4
	v_mov_b32_e32 v65, v4
	v_mov_b32_e32 v66, v4
	v_mov_b32_e32 v67, v4
	v_mov_b32_e32 v84, v4
	v_mov_b32_e32 v85, v4
	v_mov_b32_e32 v86, v4
	v_mov_b32_e32 v87, v4
	v_mov_b32_e32 v80, v4
	v_mov_b32_e32 v81, v4
	v_mov_b32_e32 v82, v4
	v_mov_b32_e32 v83, v4
	v_mov_b32_e32 v100, v4
	v_mov_b32_e32 v101, v4
	v_mov_b32_e32 v102, v4
	v_mov_b32_e32 v103, v4
	v_mov_b32_e32 v96, v4
	v_mov_b32_e32 v97, v4
	v_mov_b32_e32 v98, v4
	v_mov_b32_e32 v99, v4
	v_mov_b32_e32 v116, v4
	v_mov_b32_e32 v117, v4
	v_mov_b32_e32 v118, v4
	v_mov_b32_e32 v119, v4
	v_mov_b32_e32 v112, v4
	v_mov_b32_e32 v113, v4
	v_mov_b32_e32 v114, v4
	v_mov_b32_e32 v115, v4
	v_mov_b32_e32 v72, v4
	v_mov_b32_e32 v73, v4
	v_mov_b32_e32 v74, v4
	v_mov_b32_e32 v75, v4
	v_mov_b32_e32 v76, v4
	v_mov_b32_e32 v77, v4
	v_mov_b32_e32 v78, v4
	v_mov_b32_e32 v79, v4
	v_mov_b32_e32 v88, v4
	v_mov_b32_e32 v89, v4
	v_mov_b32_e32 v90, v4
	v_mov_b32_e32 v91, v4
	v_mov_b32_e32 v92, v4
	v_mov_b32_e32 v93, v4
	v_mov_b32_e32 v94, v4
	v_mov_b32_e32 v95, v4
	v_mov_b32_e32 v104, v4
	v_mov_b32_e32 v105, v4
	v_mov_b32_e32 v106, v4
	v_mov_b32_e32 v107, v4
	v_mov_b32_e32 v108, v4
	v_mov_b32_e32 v109, v4
	v_mov_b32_e32 v110, v4
	v_mov_b32_e32 v111, v4
	v_mov_b32_e32 v120, v4
	v_mov_b32_e32 v121, v4
	v_mov_b32_e32 v122, v4
	v_mov_b32_e32 v123, v4
	v_mov_b32_e32 v124, v4
	v_mov_b32_e32 v125, v4
	v_mov_b32_e32 v126, v4
	v_mov_b32_e32 v127, v4
	.p2align	8
